# FFN1-out / FFN2-out K loops sweep K downwards in pairs (most recently written act columns first, for L2 residency), on v51
# speedup vs baseline: 1.0046x; 1.0046x over previous
.LBB0_455:
	s_andn2_b64 vcc, exec, s[38:39]
	s_cbranch_vccnz .LBB0_495
	v_ashrrev_i32_e32 v1, 31, v11
	v_lshrrev_b32_e32 v1, 26, v1
	v_add_u32_e32 v1, v11, v1
	v_ashrrev_i32_e32 v8, 6, v1
	v_bfe_i32 v1, v11, 27, 1
	v_lshlrev_b32_e32 v0, 4, v11
	v_lshrrev_b32_e32 v1, 22, v1
	v_add_u32_e32 v1, v0, v1
	v_and_b32_e32 v1, 0xfffffc00, v1
	v_sub_u32_e32 v1, v0, v1
	v_lshrrev_b32_e32 v2, 4, v1
	v_bitop3_b32 v1, v2, v1, 32 bitop3:0x6c
	v_ashrrev_i32_e32 v3, 31, v1
	v_lshrrev_b32_e32 v3, 26, v3
	v_lshlrev_b32_e32 v2, 3, v8
	v_add_u32_e32 v3, v1, v3
	v_readlane_b32 s20, v255, 29
	v_and_b32_e32 v2, -16, v2
	v_ashrrev_i32_e32 v10, 6, v3
	v_and_b32_e32 v3, 0xc0, v3
	v_readlane_b32 s21, v255, 30
	s_add_u32 s9, s20, 0xb00000
	v_add_u32_e32 v2, v10, v2
	v_lshlrev_b32_e32 v4, 5, v8
	v_sub_u32_e32 v1, v1, v3
	s_addc_u32 s24, s21, 0
	v_and_b32_e32 v9, 32, v4
	v_ashrrev_i16_sdwa v1, v204, sext(v1) dst_sel:DWORD dst_unused:UNUSED_PAD src0_sel:DWORD src1_sel:BYTE_0
	v_lshlrev_b32_e32 v3, 1, v2
	v_lshrrev_b32_e32 v4, 2, v2
	v_and_b32_e32 v5, 3, v10
	s_mov_b32 s21, 0xffffe0
	s_waitcnt vmcnt(4)
	v_bfe_i32 v12, v1, 0, 16
	v_and_b32_e32 v3, 24, v3
	v_and_b32_e32 v4, 4, v4
	v_and_or_b32 v5, v2, s21, v5
	s_movk_i32 s20, 0xb00
	v_add_u32_e32 v1, v9, v12
	v_or3_b32 v3, v5, v4, v3
	v_mul_lo_u32 v2, v2, s20
	v_add_lshl_u32 v156, v1, v2, 1
	v_mul_u32_u24_e32 v2, 0xb00, v3
	v_add_u32_e32 v0, 0x2000, v0
	v_add_lshl_u32 v158, v2, v1, 1
	v_ashrrev_i32_e32 v1, 31, v0
	v_lshrrev_b32_e32 v1, 22, v1
	v_add_u32_e32 v1, v0, v1
	v_ashrrev_i32_e32 v13, 10, v1
	v_mul_i32_i24_e32 v1, 0x400, v13
	v_sub_u32_e32 v0, v0, v1
	v_lshrrev_b32_e32 v1, 4, v0
	v_bitop3_b32 v0, v1, v0, 32 bitop3:0x6c
	v_ashrrev_i32_e32 v2, 31, v0
	v_lshrrev_b32_e32 v2, 26, v2
	v_lshlrev_b32_e32 v1, 3, v13
	v_add_u32_e32 v2, v0, v2
	v_and_b32_e32 v1, -16, v1
	v_ashrrev_i32_e32 v15, 6, v2
	s_ashr_i32 s6, s44, 6
	v_add_u32_e32 v1, v15, v1
	v_lshlrev_b32_e32 v3, 5, v13
	v_and_b32_e32 v2, 0xc0, v2
	v_and_b32_e32 v4, 3, v15
	v_and_b32_e32 v14, 32, v3
	v_sub_u32_e32 v0, v0, v2
	v_lshlrev_b32_e32 v2, 1, v1
	v_lshrrev_b32_e32 v3, 2, v1
	v_and_or_b32 v4, v1, s21, v4
	v_mul_lo_u32 v1, v1, s20
	s_ashr_i32 s20, s44, 8
	s_lshl_b32 s58, s6, 10
	s_mul_i32 s27, s18, 0x160000
	v_ashrrev_i16_sdwa v0, v204, sext(v0) dst_sel:DWORD dst_unused:UNUSED_PAD src0_sel:DWORD src1_sel:BYTE_0
	s_mul_hi_i32 s26, s18, 0x160000
	s_add_u32 s52, s9, s27
	s_waitcnt vmcnt(3)
	v_bfe_i32 v16, v0, 0, 16
	v_and_b32_e32 v2, 24, v2
	v_and_b32_e32 v3, 4, v3
	s_addc_u32 s53, s24, s26
	s_add_u32 s52, s52, 0x1500
	s_addc_u32 s53, s53, 0
	s_add_i32 s59, s58, 0
	v_add_u32_e32 v0, v14, v16
	v_or3_b32 v2, v4, v3, v2
	s_add_i32 m0, s59, 0x10000
	v_add_lshl_u32 v160, v0, v1, 1
	v_mul_u32_u24_e32 v1, 0xb00, v2
	global_load_lds_dwordx4 v158, s[52:53]
	s_add_i32 m0, s59, 0x12000
	v_add_lshl_u32 v162, v1, v0, 1
	s_add_u32 s26, s52, 0xb0000
	global_load_lds_dwordx4 v162, s[52:53]
	s_addc_u32 s27, s53, 0
	s_add_i32 m0, s59, 0x14000
	s_mul_i32 s37, s33, 0x160000
	global_load_lds_dwordx4 v158, s[26:27]
	s_add_i32 m0, s59, 0x16000
	s_mul_hi_i32 s21, s33, 0x160000
	s_add_u32 s50, s12, s37
	s_addc_u32 s51, s13, s21
	s_add_u32 s50, s50, 0x1500
	s_addc_u32 s51, s51, 0
	s_add_i32 s60, s59, 0x2000
	global_load_lds_dwordx4 v162, s[26:27]
	s_mov_b32 m0, s59
	s_add_u32 s26, s50, 0xb0000
	global_load_lds_dwordx4 v156, s[50:51]
	s_mov_b32 m0, s60
	s_addc_u32 s27, s51, 0
	s_add_i32 s61, s59, 0x4000
	global_load_lds_dwordx4 v160, s[50:51]
	s_mov_b32 m0, s61
	s_add_i32 s62, s59, 0x6000
	global_load_lds_dwordx4 v156, s[26:27]
	s_mov_b32 m0, s62
	v_mov_b32_e32 v159, v49
	global_load_lds_dwordx4 v160, s[26:27]
	v_mov_b32_e32 v163, v49
	v_mov_b32_e32 v157, v49
	v_mov_b32_e32 v161, v49
	s_cmp_eq_u32 s20, 1
	v_lshl_add_u64 v[6:7], s[52:53], 0, v[158:159]
	v_lshl_add_u64 v[4:5], s[52:53], 0, v[162:163]
	v_lshl_add_u64 v[0:1], s[50:51], 0, v[156:157]
	s_cselect_b64 s[42:43], -1, 0
	s_cmp_lg_u32 s20, 1
	v_lshl_add_u64 v[2:3], s[50:51], 0, v[160:161]
	s_cbranch_scc1 .LBB0_458
	s_barrier

.LBB0_467:
	v_cndmask_b32_e64 v0, 0, 1, s[46:47]
	v_cmp_ne_u32_e64 s[40:41], 1, v0
	s_andn2_b64 vcc, exec, s[46:47]
	s_mov_b64 s[46:47], s[50:51]
	s_cbranch_vccnz .LBB0_469
	s_mul_i32 s20, s68, 0x160000
	s_mul_hi_i32 s6, s68, 0x160000
	s_add_u32 s46, s12, s20
	s_addc_u32 s47, s13, s6
	s_add_u32 s46, s46, 0x1500
	s_addc_u32 s47, s47, 0
.LBB0_469:
	s_and_b64 vcc, exec, s[40:41]
	s_mov_b64 s[48:49], s[52:53]
	s_cbranch_vccnz .LBB0_471
	s_mul_i32 s20, s67, 0x160000
	s_mul_hi_i32 s6, s67, 0x160000
	s_add_u32 s48, s9, s20
	s_addc_u32 s49, s24, s6
	s_add_u32 s48, s48, 0x1500
	s_addc_u32 s49, s49, 0
.LBB0_471:
	s_add_u32 s69, s52, 0xffffff00
	v_mov_b32_e32 v0, 0
	s_addc_u32 s70, s53, -1
	s_mov_b32 s71, -2
	v_mov_b32_e32 v1, v0
	v_mov_b32_e32 v2, v0
	v_mov_b32_e32 v3, v0
	v_mov_b32_e32 v4, v0
	v_mov_b32_e32 v5, v0
	v_mov_b32_e32 v6, v0
	v_mov_b32_e32 v7, v0
	v_mov_b32_e32 v16, v0
	v_mov_b32_e32 v17, v0
	v_mov_b32_e32 v18, v0
	v_mov_b32_e32 v19, v0
	v_mov_b32_e32 v20, v0
	v_mov_b32_e32 v21, v0
	v_mov_b32_e32 v22, v0
	v_mov_b32_e32 v23, v0
	v_mov_b32_e32 v32, v0
	v_mov_b32_e32 v33, v0
	v_mov_b32_e32 v34, v0
	v_mov_b32_e32 v35, v0
	v_mov_b32_e32 v36, v0
	v_mov_b32_e32 v37, v0
	v_mov_b32_e32 v38, v0
	v_mov_b32_e32 v39, v0
	v_mov_b32_e32 v50, v0
	v_mov_b32_e32 v51, v0
	v_mov_b32_e32 v52, v0
	v_mov_b32_e32 v53, v0
	v_mov_b32_e32 v54, v0
	v_mov_b32_e32 v55, v0
	v_mov_b32_e32 v56, v0
	v_mov_b32_e32 v57, v0
	v_mov_b32_e32 v8, v0
	v_mov_b32_e32 v9, v0
	v_mov_b32_e32 v10, v0
	v_mov_b32_e32 v11, v0
	v_mov_b32_e32 v12, v0
	v_mov_b32_e32 v13, v0
	v_mov_b32_e32 v14, v0
	v_mov_b32_e32 v15, v0
	v_mov_b32_e32 v24, v0
	v_mov_b32_e32 v25, v0
	v_mov_b32_e32 v26, v0
	v_mov_b32_e32 v27, v0
	v_mov_b32_e32 v28, v0
	v_mov_b32_e32 v29, v0
	v_mov_b32_e32 v30, v0
	v_mov_b32_e32 v31, v0
	v_mov_b32_e32 v40, v0
	v_mov_b32_e32 v41, v0
	v_mov_b32_e32 v42, v0
	v_mov_b32_e32 v43, v0
	v_mov_b32_e32 v44, v0
	v_mov_b32_e32 v45, v0
	v_mov_b32_e32 v46, v0
	v_mov_b32_e32 v47, v0
	v_mov_b32_e32 v58, v0
	v_mov_b32_e32 v59, v0
	v_mov_b32_e32 v60, v0
	v_mov_b32_e32 v61, v0
	v_mov_b32_e32 v62, v0
	v_mov_b32_e32 v63, v0
	v_mov_b32_e32 v64, v0
	v_mov_b32_e32 v65, v0
	v_mov_b32_e32 v66, v0
	v_mov_b32_e32 v67, v0
	v_mov_b32_e32 v68, v0
	v_mov_b32_e32 v69, v0
	v_mov_b32_e32 v70, v0
	v_mov_b32_e32 v71, v0
	v_mov_b32_e32 v72, v0
	v_mov_b32_e32 v73, v0
	v_mov_b32_e32 v82, v0
	v_mov_b32_e32 v83, v0
	v_mov_b32_e32 v84, v0
	v_mov_b32_e32 v85, v0
	v_mov_b32_e32 v86, v0
	v_mov_b32_e32 v87, v0
	v_mov_b32_e32 v88, v0
	v_mov_b32_e32 v89, v0
	v_mov_b32_e32 v98, v0
	v_mov_b32_e32 v99, v0
	v_mov_b32_e32 v100, v0
	v_mov_b32_e32 v101, v0
	v_mov_b32_e32 v102, v0
	v_mov_b32_e32 v103, v0
	v_mov_b32_e32 v104, v0
	v_mov_b32_e32 v105, v0
	v_mov_b32_e32 v114, v0
	v_mov_b32_e32 v115, v0
	v_mov_b32_e32 v116, v0
	v_mov_b32_e32 v117, v0
	v_mov_b32_e32 v118, v0
	v_mov_b32_e32 v119, v0
	v_mov_b32_e32 v120, v0
	v_mov_b32_e32 v121, v0
	v_mov_b32_e32 v74, v0
	v_mov_b32_e32 v75, v0
	v_mov_b32_e32 v76, v0
	v_mov_b32_e32 v77, v0
	v_mov_b32_e32 v78, v0
	v_mov_b32_e32 v79, v0
	v_mov_b32_e32 v80, v0
	v_mov_b32_e32 v81, v0
	v_mov_b32_e32 v90, v0
	v_mov_b32_e32 v91, v0
	v_mov_b32_e32 v92, v0
	v_mov_b32_e32 v93, v0
	v_mov_b32_e32 v94, v0
	v_mov_b32_e32 v95, v0
	v_mov_b32_e32 v96, v0
	v_mov_b32_e32 v97, v0
	v_mov_b32_e32 v106, v0
	v_mov_b32_e32 v107, v0
	v_mov_b32_e32 v108, v0
	v_mov_b32_e32 v109, v0
	v_mov_b32_e32 v110, v0
	v_mov_b32_e32 v111, v0
	v_mov_b32_e32 v112, v0
	v_mov_b32_e32 v113, v0
	v_mov_b32_e32 v126, v0
	v_mov_b32_e32 v127, v0
	v_mov_b32_e32 v128, v0
	v_mov_b32_e32 v129, v0
	v_mov_b32_e32 v134, v0
	v_mov_b32_e32 v135, v0
	v_mov_b32_e32 v136, v0
	v_mov_b32_e32 v137, v0
.LBB0_472:
	s_add_u32 s52, s50, 0xffffff00
	s_addc_u32 s53, s51, -1
	s_add_i32 s6, 0, 0x10000
	s_cmp_eq_u32 s71, 40
	s_cselect_b32 s57, s47, s53
	s_cselect_b32 s56, s46, s52
	v_add_u32_e32 v48, s6, v183
	s_cselect_b32 s55, s49, s70
	s_cselect_b32 s54, s48, s69
	s_add_i32 s26, 0, 0x14000
	ds_read_b128 v[122:125], v48
	ds_read_b128 v[130:133], v48 offset:1024
	ds_read_b128 v[138:141], v48 offset:2048
	ds_read_b128 v[142:145], v48 offset:3072
	v_add_u32_e32 v48, s26, v183
	ds_read_b128 v[146:149], v48
	ds_read_b128 v[150:153], v48 offset:1024
	ds_read_b128 v[168:171], v48 offset:2048
	ds_read_b128 v[172:175], v48 offset:3072
	v_lshl_add_u64 v[180:181], s[50:51], 0, v[164:165]
	s_add_i32 m0, s59, 0xc000
	ds_read_b128 v[176:179], v185
	ds_read_b128 v[186:189], v185 offset:1024
	ds_read_b128 v[190:193], v185 offset:2048
	ds_read_b128 v[194:197], v185 offset:3072
	ds_read_b128 v[198:201], v185 offset:4096
	ds_read_b128 v[216:219], v185 offset:5120
	ds_read_b128 v[220:223], v185 offset:6144
	ds_read_b128 v[224:227], v185 offset:7168
	global_load_lds_dwordx4 v[180:181], off
	v_lshl_add_u64 v[180:181], s[50:51], 0, v[166:167]
	s_add_i32 m0, s59, 0xe000
	s_nop 0
	global_load_lds_dwordx4 v[180:181], off
	s_waitcnt vmcnt(8)
	s_waitcnt lgkmcnt(0)
	s_barrier
	s_setprio 1
	v_mfma_f32_16x16x32_bf16 v[134:137], v[122:125], v[176:179], v[134:137]
	v_mfma_f32_16x16x32_bf16 v[126:129], v[138:141], v[176:179], v[126:129]
	v_mfma_f32_16x16x32_bf16 v[110:113], v[122:125], v[190:193], v[110:113]
	v_mfma_f32_16x16x32_bf16 v[106:109], v[138:141], v[190:193], v[106:109]
	v_mfma_f32_16x16x32_bf16 v[94:97], v[122:125], v[198:201], v[94:97]
	v_mfma_f32_16x16x32_bf16 v[90:93], v[138:141], v[198:201], v[90:93]
	v_mfma_f32_16x16x32_bf16 v[78:81], v[122:125], v[220:223], v[78:81]
	v_mfma_f32_16x16x32_bf16 v[74:77], v[138:141], v[220:223], v[74:77]
	v_mfma_f32_16x16x32_bf16 v[134:137], v[130:133], v[186:189], v[134:137]
	v_mfma_f32_16x16x32_bf16 v[126:129], v[142:145], v[186:189], v[126:129]
	v_mfma_f32_16x16x32_bf16 v[110:113], v[130:133], v[194:197], v[110:113]
	v_mfma_f32_16x16x32_bf16 v[106:109], v[142:145], v[194:197], v[106:109]
	v_mfma_f32_16x16x32_bf16 v[94:97], v[130:133], v[216:219], v[94:97]
	v_mfma_f32_16x16x32_bf16 v[90:93], v[142:145], v[216:219], v[90:93]
	v_mfma_f32_16x16x32_bf16 v[78:81], v[130:133], v[224:227], v[78:81]
	v_mfma_f32_16x16x32_bf16 v[74:77], v[142:145], v[224:227], v[74:77]
	v_mfma_f32_16x16x32_bf16 v[118:121], v[146:149], v[176:179], v[118:121]
	v_mfma_f32_16x16x32_bf16 v[114:117], v[168:171], v[176:179], v[114:117]
	v_mfma_f32_16x16x32_bf16 v[102:105], v[146:149], v[190:193], v[102:105]
	v_mfma_f32_16x16x32_bf16 v[98:101], v[168:171], v[190:193], v[98:101]
	v_mfma_f32_16x16x32_bf16 v[86:89], v[146:149], v[198:201], v[86:89]
	v_mfma_f32_16x16x32_bf16 v[82:85], v[168:171], v[198:201], v[82:85]
	v_mfma_f32_16x16x32_bf16 v[70:73], v[146:149], v[220:223], v[70:73]
	v_mfma_f32_16x16x32_bf16 v[66:69], v[168:171], v[220:223], v[66:69]
	v_mfma_f32_16x16x32_bf16 v[118:121], v[150:153], v[186:189], v[118:121]
	v_mfma_f32_16x16x32_bf16 v[114:117], v[172:175], v[186:189], v[114:117]
	v_mfma_f32_16x16x32_bf16 v[102:105], v[150:153], v[194:197], v[102:105]
	v_mfma_f32_16x16x32_bf16 v[98:101], v[172:175], v[194:197], v[98:101]
	v_mfma_f32_16x16x32_bf16 v[86:89], v[150:153], v[216:219], v[86:89]
	v_mfma_f32_16x16x32_bf16 v[82:85], v[172:175], v[216:219], v[82:85]
	v_mfma_f32_16x16x32_bf16 v[70:73], v[150:153], v[224:227], v[70:73]
	v_mfma_f32_16x16x32_bf16 v[66:69], v[172:175], v[224:227], v[66:69]
	s_setprio 0
	s_barrier
	s_add_i32 s6, s6, s58
	v_lshl_add_u64 v[180:181], s[54:55], 0, v[158:159]
	s_mov_b32 m0, s6
	ds_read_b128 v[176:179], v185 offset:16384
	ds_read_b128 v[186:189], v185 offset:17408
	ds_read_b128 v[190:193], v185 offset:18432
	ds_read_b128 v[194:197], v185 offset:19456
	ds_read_b128 v[198:201], v185 offset:20480
	ds_read_b128 v[216:219], v185 offset:21504
	ds_read_b128 v[220:223], v185 offset:22528
	ds_read_b128 v[224:227], v185 offset:23552
	global_load_lds_dwordx4 v[180:181], off
	s_add_i32 m0, s6, 0x2000
	s_add_u32 s20, s54, 0xb0000
	v_lshl_add_u64 v[202:203], s[54:55], 0, v[162:163]
	s_addc_u32 s21, s55, 0
	s_add_i32 s6, s26, s58
	global_load_lds_dwordx4 v[202:203], off
	v_lshl_add_u64 v[228:229], s[20:21], 0, v[158:159]
	s_mov_b32 m0, s6
	v_lshl_add_u64 v[230:231], s[56:57], 0, v[160:161]
	global_load_lds_dwordx4 v[228:229], off
	v_lshl_add_u64 v[228:229], s[20:21], 0, v[162:163]
	s_add_i32 m0, s6, 0x2000
	s_nop 0
	global_load_lds_dwordx4 v[228:229], off
	v_lshl_add_u64 v[228:229], s[56:57], 0, v[156:157]
	s_mov_b32 m0, s59
	s_nop 0
	global_load_lds_dwordx4 v[228:229], off
	s_mov_b32 m0, s60
	s_nop 0
	global_load_lds_dwordx4 v[230:231], off
	s_waitcnt vmcnt(8)
	s_waitcnt lgkmcnt(0)
	s_barrier
	s_setprio 1
	v_mfma_f32_16x16x32_bf16 v[62:65], v[122:125], v[176:179], v[62:65]
	v_mfma_f32_16x16x32_bf16 v[58:61], v[138:141], v[176:179], v[58:61]
	v_mfma_f32_16x16x32_bf16 v[44:47], v[122:125], v[190:193], v[44:47]
	v_mfma_f32_16x16x32_bf16 v[40:43], v[138:141], v[190:193], v[40:43]
	v_mfma_f32_16x16x32_bf16 v[28:31], v[122:125], v[198:201], v[28:31]
	v_mfma_f32_16x16x32_bf16 v[24:27], v[138:141], v[198:201], v[24:27]
	v_mfma_f32_16x16x32_bf16 v[12:15], v[122:125], v[220:223], v[12:15]
	v_mfma_f32_16x16x32_bf16 v[8:11], v[138:141], v[220:223], v[8:11]
	v_mfma_f32_16x16x32_bf16 v[62:65], v[130:133], v[186:189], v[62:65]
	v_mfma_f32_16x16x32_bf16 v[58:61], v[142:145], v[186:189], v[58:61]
	v_mfma_f32_16x16x32_bf16 v[44:47], v[130:133], v[194:197], v[44:47]
	v_mfma_f32_16x16x32_bf16 v[40:43], v[142:145], v[194:197], v[40:43]
	v_mfma_f32_16x16x32_bf16 v[28:31], v[130:133], v[216:219], v[28:31]
	v_mfma_f32_16x16x32_bf16 v[24:27], v[142:145], v[216:219], v[24:27]
	v_mfma_f32_16x16x32_bf16 v[12:15], v[130:133], v[224:227], v[12:15]
	v_mfma_f32_16x16x32_bf16 v[8:11], v[142:145], v[224:227], v[8:11]
	v_mfma_f32_16x16x32_bf16 v[54:57], v[146:149], v[176:179], v[54:57]
	v_mfma_f32_16x16x32_bf16 v[50:53], v[168:171], v[176:179], v[50:53]
	v_mfma_f32_16x16x32_bf16 v[36:39], v[146:149], v[190:193], v[36:39]
	v_mfma_f32_16x16x32_bf16 v[32:35], v[168:171], v[190:193], v[32:35]
	v_mfma_f32_16x16x32_bf16 v[20:23], v[146:149], v[198:201], v[20:23]
	v_mfma_f32_16x16x32_bf16 v[16:19], v[168:171], v[198:201], v[16:19]
	v_mfma_f32_16x16x32_bf16 v[4:7], v[146:149], v[220:223], v[4:7]
	v_mfma_f32_16x16x32_bf16 v[0:3], v[168:171], v[220:223], v[0:3]
	v_mfma_f32_16x16x32_bf16 v[54:57], v[150:153], v[186:189], v[54:57]
	v_mfma_f32_16x16x32_bf16 v[50:53], v[172:175], v[186:189], v[50:53]
	v_mfma_f32_16x16x32_bf16 v[36:39], v[150:153], v[194:197], v[36:39]
	v_mfma_f32_16x16x32_bf16 v[32:35], v[172:175], v[194:197], v[32:35]
	v_mfma_f32_16x16x32_bf16 v[20:23], v[150:153], v[216:219], v[20:23]
	v_mfma_f32_16x16x32_bf16 v[16:19], v[172:175], v[216:219], v[16:19]
	v_mfma_f32_16x16x32_bf16 v[4:7], v[150:153], v[224:227], v[4:7]
	v_mfma_f32_16x16x32_bf16 v[0:3], v[172:175], v[224:227], v[0:3]
	s_setprio 0
	s_barrier
	s_add_i32 s6, 0, 0x18000
	v_add_u32_e32 v48, s6, v183
	s_add_i32 s26, 0, 0x1c000
	ds_read_b128 v[122:125], v48
	ds_read_b128 v[130:133], v48 offset:1024
	ds_read_b128 v[138:141], v48 offset:2048
	ds_read_b128 v[142:145], v48 offset:3072
	v_add_u32_e32 v48, s26, v183
	ds_read_b128 v[146:149], v48
	ds_read_b128 v[150:153], v48 offset:1024
	ds_read_b128 v[168:171], v48 offset:2048
	ds_read_b128 v[172:175], v48 offset:3072
	s_add_u32 s20, s56, 0xb0000
	s_addc_u32 s21, s57, 0
	s_mov_b32 m0, s61
	v_lshl_add_u64 v[232:233], s[20:21], 0, v[156:157]
	ds_read_b128 v[176:179], v185 offset:32768
	ds_read_b128 v[186:189], v185 offset:33792
	ds_read_b128 v[190:193], v185 offset:34816
	ds_read_b128 v[194:197], v185 offset:35840
	ds_read_b128 v[198:201], v185 offset:36864
	ds_read_b128 v[216:219], v185 offset:37888
	ds_read_b128 v[220:223], v185 offset:38912
	ds_read_b128 v[224:227], v185 offset:39936
	global_load_lds_dwordx4 v[232:233], off
	v_lshl_add_u64 v[232:233], s[20:21], 0, v[160:161]
	s_mov_b32 m0, s62
	s_nop 0
	global_load_lds_dwordx4 v[232:233], off
	s_waitcnt vmcnt(8)
	s_waitcnt lgkmcnt(0)
	s_barrier
	s_setprio 1
	v_mfma_f32_16x16x32_bf16 v[134:137], v[122:125], v[176:179], v[134:137]
	v_mfma_f32_16x16x32_bf16 v[126:129], v[138:141], v[176:179], v[126:129]
	v_mfma_f32_16x16x32_bf16 v[110:113], v[122:125], v[190:193], v[110:113]
	v_mfma_f32_16x16x32_bf16 v[106:109], v[138:141], v[190:193], v[106:109]
	v_mfma_f32_16x16x32_bf16 v[94:97], v[122:125], v[198:201], v[94:97]
	v_mfma_f32_16x16x32_bf16 v[90:93], v[138:141], v[198:201], v[90:93]
	v_mfma_f32_16x16x32_bf16 v[78:81], v[122:125], v[220:223], v[78:81]
	v_mfma_f32_16x16x32_bf16 v[74:77], v[138:141], v[220:223], v[74:77]
	v_mfma_f32_16x16x32_bf16 v[134:137], v[130:133], v[186:189], v[134:137]
	v_mfma_f32_16x16x32_bf16 v[126:129], v[142:145], v[186:189], v[126:129]
	v_mfma_f32_16x16x32_bf16 v[110:113], v[130:133], v[194:197], v[110:113]
	v_mfma_f32_16x16x32_bf16 v[106:109], v[142:145], v[194:197], v[106:109]
	v_mfma_f32_16x16x32_bf16 v[94:97], v[130:133], v[216:219], v[94:97]
	v_mfma_f32_16x16x32_bf16 v[90:93], v[142:145], v[216:219], v[90:93]
	v_mfma_f32_16x16x32_bf16 v[78:81], v[130:133], v[224:227], v[78:81]
	v_mfma_f32_16x16x32_bf16 v[74:77], v[142:145], v[224:227], v[74:77]
	v_mfma_f32_16x16x32_bf16 v[118:121], v[146:149], v[176:179], v[118:121]
	v_mfma_f32_16x16x32_bf16 v[114:117], v[168:171], v[176:179], v[114:117]
	v_mfma_f32_16x16x32_bf16 v[102:105], v[146:149], v[190:193], v[102:105]
	v_mfma_f32_16x16x32_bf16 v[98:101], v[168:171], v[190:193], v[98:101]
	v_mfma_f32_16x16x32_bf16 v[86:89], v[146:149], v[198:201], v[86:89]
	v_mfma_f32_16x16x32_bf16 v[82:85], v[168:171], v[198:201], v[82:85]
	v_mfma_f32_16x16x32_bf16 v[70:73], v[146:149], v[220:223], v[70:73]
	v_mfma_f32_16x16x32_bf16 v[66:69], v[168:171], v[220:223], v[66:69]
	v_mfma_f32_16x16x32_bf16 v[118:121], v[150:153], v[186:189], v[118:121]
	v_mfma_f32_16x16x32_bf16 v[114:117], v[172:175], v[186:189], v[114:117]
	v_mfma_f32_16x16x32_bf16 v[102:105], v[150:153], v[194:197], v[102:105]
	v_mfma_f32_16x16x32_bf16 v[98:101], v[172:175], v[194:197], v[98:101]
	v_mfma_f32_16x16x32_bf16 v[86:89], v[150:153], v[216:219], v[86:89]
	v_mfma_f32_16x16x32_bf16 v[82:85], v[172:175], v[216:219], v[82:85]
	v_mfma_f32_16x16x32_bf16 v[70:73], v[150:153], v[224:227], v[70:73]
	v_mfma_f32_16x16x32_bf16 v[66:69], v[172:175], v[224:227], v[66:69]
	s_setprio 0
	s_barrier
	s_add_i32 s6, s6, s58
	v_lshl_add_u64 v[180:181], v[180:181], 0, s[30:31]
	s_mov_b32 m0, s6
	ds_read_b128 v[176:179], v185 offset:49152
	ds_read_b128 v[186:189], v185 offset:50176
	ds_read_b128 v[190:193], v185 offset:51200
	ds_read_b128 v[194:197], v185 offset:52224
	ds_read_b128 v[198:201], v185 offset:53248
	ds_read_b128 v[216:219], v185 offset:54272
	ds_read_b128 v[220:223], v185 offset:55296
	ds_read_b128 v[224:227], v185 offset:56320
	global_load_lds_dwordx4 v[180:181], off
	s_add_i32 m0, s6, 0x2000
	s_add_u32 s20, s54, 0xb0080
	v_lshl_add_u64 v[180:181], v[202:203], 0, s[30:31]
	s_addc_u32 s21, s55, 0
	s_add_i32 s6, s26, s58
	global_load_lds_dwordx4 v[180:181], off
	v_lshl_add_u64 v[180:181], s[20:21], 0, v[158:159]
	s_mov_b32 m0, s6
	s_nop 0
	global_load_lds_dwordx4 v[180:181], off
	v_lshl_add_u64 v[180:181], s[20:21], 0, v[162:163]
	s_add_i32 m0, s6, 0x2000
	s_nop 0
	global_load_lds_dwordx4 v[180:181], off
	v_lshl_add_u64 v[180:181], v[228:229], 0, s[30:31]
	s_mov_b32 m0, s63
	s_nop 0
	global_load_lds_dwordx4 v[180:181], off
	v_lshl_add_u64 v[180:181], v[230:231], 0, s[30:31]
	s_mov_b32 m0, s64
	s_nop 0
	global_load_lds_dwordx4 v[180:181], off
	s_waitcnt vmcnt(8)
	s_waitcnt lgkmcnt(0)
	s_barrier
	s_setprio 1
	v_mfma_f32_16x16x32_bf16 v[62:65], v[122:125], v[176:179], v[62:65]
	v_mfma_f32_16x16x32_bf16 v[58:61], v[138:141], v[176:179], v[58:61]
	v_mfma_f32_16x16x32_bf16 v[44:47], v[122:125], v[190:193], v[44:47]
	v_mfma_f32_16x16x32_bf16 v[40:43], v[138:141], v[190:193], v[40:43]
	v_mfma_f32_16x16x32_bf16 v[28:31], v[122:125], v[198:201], v[28:31]
	v_mfma_f32_16x16x32_bf16 v[24:27], v[138:141], v[198:201], v[24:27]
	v_mfma_f32_16x16x32_bf16 v[12:15], v[122:125], v[220:223], v[12:15]
	v_mfma_f32_16x16x32_bf16 v[8:11], v[138:141], v[220:223], v[8:11]
	v_mfma_f32_16x16x32_bf16 v[62:65], v[130:133], v[186:189], v[62:65]
	v_mfma_f32_16x16x32_bf16 v[58:61], v[142:145], v[186:189], v[58:61]
	v_mfma_f32_16x16x32_bf16 v[44:47], v[130:133], v[194:197], v[44:47]
	v_mfma_f32_16x16x32_bf16 v[40:43], v[142:145], v[194:197], v[40:43]
	v_mfma_f32_16x16x32_bf16 v[28:31], v[130:133], v[216:219], v[28:31]
	v_mfma_f32_16x16x32_bf16 v[24:27], v[142:145], v[216:219], v[24:27]
	v_mfma_f32_16x16x32_bf16 v[12:15], v[130:133], v[224:227], v[12:15]
	v_mfma_f32_16x16x32_bf16 v[8:11], v[142:145], v[224:227], v[8:11]
	v_mfma_f32_16x16x32_bf16 v[54:57], v[146:149], v[176:179], v[54:57]
	v_mfma_f32_16x16x32_bf16 v[50:53], v[168:171], v[176:179], v[50:53]
	v_mfma_f32_16x16x32_bf16 v[36:39], v[146:149], v[190:193], v[36:39]
	v_mfma_f32_16x16x32_bf16 v[32:35], v[168:171], v[190:193], v[32:35]
	v_mfma_f32_16x16x32_bf16 v[20:23], v[146:149], v[198:201], v[20:23]
	v_mfma_f32_16x16x32_bf16 v[16:19], v[168:171], v[198:201], v[16:19]
	v_mfma_f32_16x16x32_bf16 v[4:7], v[146:149], v[220:223], v[4:7]
	v_mfma_f32_16x16x32_bf16 v[0:3], v[168:171], v[220:223], v[0:3]
	v_mfma_f32_16x16x32_bf16 v[54:57], v[150:153], v[186:189], v[54:57]
	v_mfma_f32_16x16x32_bf16 v[50:53], v[172:175], v[186:189], v[50:53]
	v_mfma_f32_16x16x32_bf16 v[36:39], v[150:153], v[194:197], v[36:39]
	v_mfma_f32_16x16x32_bf16 v[32:35], v[172:175], v[194:197], v[32:35]
	v_mfma_f32_16x16x32_bf16 v[20:23], v[150:153], v[216:219], v[20:23]
	v_mfma_f32_16x16x32_bf16 v[16:19], v[172:175], v[216:219], v[16:19]
	v_mfma_f32_16x16x32_bf16 v[4:7], v[150:153], v[224:227], v[4:7]
	v_mfma_f32_16x16x32_bf16 v[0:3], v[172:175], v[224:227], v[0:3]
	s_setprio 0
	s_barrier
	s_add_i32 s71, s71, 2
	s_add_u32 s69, s69, 0xffffff00
	s_addc_u32 s70, s70, -1
	s_cmp_gt_u32 s71, 41
	s_mov_b64 s[50:51], s[52:53]
	s_cbranch_scc0 .LBB0_472
	s_and_b64 vcc, exec, s[44:45]
	s_cbranch_vccz .LBB0_475
	s_barrier

.LBB0_1961:
	s_andn2_b64 vcc, exec, s[2:3]
	s_cbranch_vccnz .LBB0_2001
	v_ashrrev_i32_e32 v1, 31, v12
	v_lshrrev_b32_e32 v1, 26, v1
	v_add_u32_e32 v1, v12, v1
	v_ashrrev_i32_e32 v8, 6, v1
	v_bfe_i32 v1, v12, 27, 1
	v_lshlrev_b32_e32 v0, 4, v12
	v_lshrrev_b32_e32 v1, 22, v1
	v_add_u32_e32 v1, v0, v1
	v_and_b32_e32 v1, 0xfffffc00, v1
	v_sub_u32_e32 v1, v0, v1
	v_lshrrev_b32_e32 v2, 4, v1
	v_bitop3_b32 v1, v2, v1, 32 bitop3:0x6c
	v_ashrrev_i32_e32 v3, 31, v1
	v_lshrrev_b32_e32 v3, 26, v3
	v_lshlrev_b32_e32 v2, 3, v8
	v_add_u32_e32 v3, v1, v3
	v_readlane_b32 s2, v255, 29
	v_and_b32_e32 v2, -16, v2
	v_ashrrev_i32_e32 v10, 6, v3
	v_and_b32_e32 v3, 0xc0, v3
	v_readlane_b32 s3, v255, 30
	s_add_u32 s8, s2, 0x1b80000
	v_add_u32_e32 v2, v10, v2
	v_lshlrev_b32_e32 v4, 5, v8
	v_sub_u32_e32 v1, v1, v3
	s_addc_u32 s9, s3, 0
	v_and_b32_e32 v9, 32, v4
	v_ashrrev_i16_sdwa v1, v204, sext(v1) dst_sel:DWORD dst_unused:UNUSED_PAD src0_sel:DWORD src1_sel:BYTE_0
	v_lshlrev_b32_e32 v3, 1, v2
	v_lshrrev_b32_e32 v4, 2, v2
	v_and_b32_e32 v5, 3, v10
	s_mov_b32 s3, 0xffffe0
	v_bfe_i32 v11, v1, 0, 16
	v_and_b32_e32 v3, 24, v3
	v_and_b32_e32 v4, 4, v4
	v_and_or_b32 v5, v2, s3, v5
	s_movk_i32 s2, 0xb00
	v_add_u32_e32 v1, v9, v11
	v_or3_b32 v3, v5, v4, v3
	v_mul_lo_u32 v2, v2, s2
	v_add_lshl_u32 v156, v1, v2, 1
	v_mul_u32_u24_e32 v2, 0xb00, v3
	v_add_u32_e32 v0, 0x2000, v0
	v_add_lshl_u32 v158, v2, v1, 1
	v_ashrrev_i32_e32 v1, 31, v0
	v_lshrrev_b32_e32 v1, 22, v1
	v_add_u32_e32 v1, v0, v1
	v_ashrrev_i32_e32 v13, 10, v1
	v_mul_i32_i24_e32 v1, 0x400, v13
	v_sub_u32_e32 v0, v0, v1
	v_lshrrev_b32_e32 v1, 4, v0
	v_bitop3_b32 v0, v1, v0, 32 bitop3:0x6c
	v_ashrrev_i32_e32 v2, 31, v0
	v_lshrrev_b32_e32 v2, 26, v2
	v_lshlrev_b32_e32 v1, 3, v13
	v_add_u32_e32 v2, v0, v2
	v_and_b32_e32 v1, -16, v1
	v_ashrrev_i32_e32 v15, 6, v2
	s_ashr_i32 s6, s40, 6
	v_add_u32_e32 v1, v15, v1
	v_and_b32_e32 v2, 0xc0, v2
	v_and_b32_e32 v4, 3, v15
	v_lshlrev_b32_e32 v3, 5, v13
	v_sub_u32_e32 v0, v0, v2
	v_and_or_b32 v4, v1, s3, v4
	s_ashr_i32 s20, s40, 8
	s_lshl_b32 s24, s6, 10
	s_mul_i32 s3, s18, 0x160000
	v_and_b32_e32 v14, 32, v3
	v_ashrrev_i16_sdwa v0, v204, sext(v0) dst_sel:DWORD dst_unused:UNUSED_PAD src0_sel:DWORD src1_sel:BYTE_0
	v_lshlrev_b32_e32 v2, 1, v1
	v_lshrrev_b32_e32 v3, 2, v1
	v_mul_lo_u32 v1, v1, s2
	s_mul_hi_i32 s2, s18, 0x160000
	s_add_u32 s50, s8, s3
	s_waitcnt vmcnt(3)
	v_bfe_i32 v16, v0, 0, 16
	v_and_b32_e32 v2, 24, v2
	v_and_b32_e32 v3, 4, v3
	s_addc_u32 s51, s9, s2
	s_add_u32 s50, s50, 0x1500
	s_addc_u32 s51, s51, 0
	s_add_i32 s56, s24, 0
	v_add_u32_e32 v0, v14, v16
	v_or3_b32 v2, v4, v3, v2
	s_add_i32 m0, s56, 0x10000
	v_add_lshl_u32 v160, v0, v1, 1
	v_mul_u32_u24_e32 v1, 0xb00, v2
	global_load_lds_dwordx4 v158, s[50:51]
	s_add_i32 m0, s56, 0x12000
	v_add_lshl_u32 v162, v1, v0, 1
	s_add_u32 s2, s50, 0xb0000
	global_load_lds_dwordx4 v162, s[50:51]
	s_addc_u32 s3, s51, 0
	s_add_i32 m0, s56, 0x14000
	s_mul_i32 s26, s33, 0x160000
	global_load_lds_dwordx4 v158, s[2:3]
	s_add_i32 m0, s56, 0x16000
	s_mul_hi_i32 s21, s33, 0x160000
	s_add_u32 s48, s12, s26
	s_addc_u32 s49, s13, s21
	s_add_u32 s48, s48, 0x1500
	s_addc_u32 s49, s49, 0
	s_add_i32 s57, s56, 0x2000
	global_load_lds_dwordx4 v162, s[2:3]
	s_mov_b32 m0, s56
	s_add_u32 s2, s48, 0xb0000
	global_load_lds_dwordx4 v156, s[48:49]
	s_mov_b32 m0, s57
	s_addc_u32 s3, s49, 0
	s_add_i32 s58, s56, 0x4000
	global_load_lds_dwordx4 v160, s[48:49]
	s_mov_b32 m0, s58
	s_add_i32 s59, s56, 0x6000
	global_load_lds_dwordx4 v156, s[2:3]
	s_mov_b32 m0, s59
	v_mov_b32_e32 v159, v49
	global_load_lds_dwordx4 v160, s[2:3]
	v_mov_b32_e32 v163, v49
	v_mov_b32_e32 v157, v49
	v_mov_b32_e32 v161, v49
	s_cmp_eq_u32 s20, 1
	v_lshl_add_u64 v[6:7], s[50:51], 0, v[158:159]
	v_lshl_add_u64 v[4:5], s[50:51], 0, v[162:163]
	v_lshl_add_u64 v[0:1], s[48:49], 0, v[156:157]
	s_cselect_b64 s[2:3], -1, 0
	s_cmp_lg_u32 s20, 1
	v_lshl_add_u64 v[2:3], s[48:49], 0, v[160:161]
	s_cbranch_scc1 .LBB0_1964
	s_barrier

.LBB0_1973:
	v_cndmask_b32_e64 v0, 0, 1, s[44:45]
	v_cmp_ne_u32_e64 s[40:41], 1, v0
	s_andn2_b64 vcc, exec, s[44:45]
	s_mov_b64 s[44:45], s[48:49]
	s_cbranch_vccnz .LBB0_1975
	s_mul_i32 s20, s65, 0x160000
	s_mul_hi_i32 s6, s65, 0x160000
	s_add_u32 s44, s12, s20
	s_addc_u32 s45, s13, s6
	s_add_u32 s44, s44, 0x1500
	s_addc_u32 s45, s45, 0
.LBB0_1975:
	s_and_b64 vcc, exec, s[40:41]
	s_mov_b64 s[46:47], s[50:51]
	s_cbranch_vccnz .LBB0_1977
	s_mul_i32 s20, s64, 0x160000
	s_mul_hi_i32 s6, s64, 0x160000
	s_add_u32 s46, s8, s20
	s_addc_u32 s47, s9, s6
	s_add_u32 s46, s46, 0x1500
	s_addc_u32 s47, s47, 0
.LBB0_1977:
	s_add_u32 s66, s50, 0xffffff00
	v_mov_b32_e32 v0, 0
	s_addc_u32 s67, s51, -1
	s_mov_b32 s68, -2
	v_mov_b32_e32 v1, v0
	v_mov_b32_e32 v2, v0
	v_mov_b32_e32 v3, v0
	v_mov_b32_e32 v4, v0
	v_mov_b32_e32 v5, v0
	v_mov_b32_e32 v6, v0
	v_mov_b32_e32 v7, v0
	v_mov_b32_e32 v16, v0
	v_mov_b32_e32 v17, v0
	v_mov_b32_e32 v18, v0
	v_mov_b32_e32 v19, v0
	v_mov_b32_e32 v20, v0
	v_mov_b32_e32 v21, v0
	v_mov_b32_e32 v22, v0
	v_mov_b32_e32 v23, v0
	v_mov_b32_e32 v32, v0
	v_mov_b32_e32 v33, v0
	v_mov_b32_e32 v34, v0
	v_mov_b32_e32 v35, v0
	v_mov_b32_e32 v36, v0
	v_mov_b32_e32 v37, v0
	v_mov_b32_e32 v38, v0
	v_mov_b32_e32 v39, v0
	v_mov_b32_e32 v50, v0
	v_mov_b32_e32 v51, v0
	v_mov_b32_e32 v52, v0
	v_mov_b32_e32 v53, v0
	v_mov_b32_e32 v54, v0
	v_mov_b32_e32 v55, v0
	v_mov_b32_e32 v56, v0
	v_mov_b32_e32 v57, v0
	v_mov_b32_e32 v8, v0
	v_mov_b32_e32 v9, v0
	v_mov_b32_e32 v10, v0
	v_mov_b32_e32 v11, v0
	v_mov_b32_e32 v12, v0
	v_mov_b32_e32 v13, v0
	v_mov_b32_e32 v14, v0
	v_mov_b32_e32 v15, v0
	v_mov_b32_e32 v24, v0
	v_mov_b32_e32 v25, v0
	v_mov_b32_e32 v26, v0
	v_mov_b32_e32 v27, v0
	v_mov_b32_e32 v28, v0
	v_mov_b32_e32 v29, v0
	v_mov_b32_e32 v30, v0
	v_mov_b32_e32 v31, v0
	v_mov_b32_e32 v40, v0
	v_mov_b32_e32 v41, v0
	v_mov_b32_e32 v42, v0
	v_mov_b32_e32 v43, v0
	v_mov_b32_e32 v44, v0
	v_mov_b32_e32 v45, v0
	v_mov_b32_e32 v46, v0
	v_mov_b32_e32 v47, v0
	v_mov_b32_e32 v58, v0
	v_mov_b32_e32 v59, v0
	v_mov_b32_e32 v60, v0
	v_mov_b32_e32 v61, v0
	v_mov_b32_e32 v62, v0
	v_mov_b32_e32 v63, v0
	v_mov_b32_e32 v64, v0
	v_mov_b32_e32 v65, v0
	v_mov_b32_e32 v66, v0
	v_mov_b32_e32 v67, v0
	v_mov_b32_e32 v68, v0
	v_mov_b32_e32 v69, v0
	v_mov_b32_e32 v70, v0
	v_mov_b32_e32 v71, v0
	v_mov_b32_e32 v72, v0
	v_mov_b32_e32 v73, v0
	v_mov_b32_e32 v82, v0
	v_mov_b32_e32 v83, v0
	v_mov_b32_e32 v84, v0
	v_mov_b32_e32 v85, v0
	v_mov_b32_e32 v86, v0
	v_mov_b32_e32 v87, v0
	v_mov_b32_e32 v88, v0
	v_mov_b32_e32 v89, v0
	v_mov_b32_e32 v98, v0
	v_mov_b32_e32 v99, v0
	v_mov_b32_e32 v100, v0
	v_mov_b32_e32 v101, v0
	v_mov_b32_e32 v102, v0
	v_mov_b32_e32 v103, v0
	v_mov_b32_e32 v104, v0
	v_mov_b32_e32 v105, v0
	v_mov_b32_e32 v114, v0
	v_mov_b32_e32 v115, v0
	v_mov_b32_e32 v116, v0
	v_mov_b32_e32 v117, v0
	v_mov_b32_e32 v118, v0
	v_mov_b32_e32 v119, v0
	v_mov_b32_e32 v120, v0
	v_mov_b32_e32 v121, v0
	v_mov_b32_e32 v74, v0
	v_mov_b32_e32 v75, v0
	v_mov_b32_e32 v76, v0
	v_mov_b32_e32 v77, v0
	v_mov_b32_e32 v78, v0
	v_mov_b32_e32 v79, v0
	v_mov_b32_e32 v80, v0
	v_mov_b32_e32 v81, v0
	v_mov_b32_e32 v90, v0
	v_mov_b32_e32 v91, v0
	v_mov_b32_e32 v92, v0
	v_mov_b32_e32 v93, v0
	v_mov_b32_e32 v94, v0
	v_mov_b32_e32 v95, v0
	v_mov_b32_e32 v96, v0
	v_mov_b32_e32 v97, v0
	v_mov_b32_e32 v106, v0
	v_mov_b32_e32 v107, v0
	v_mov_b32_e32 v108, v0
	v_mov_b32_e32 v109, v0
	v_mov_b32_e32 v110, v0
	v_mov_b32_e32 v111, v0
	v_mov_b32_e32 v112, v0
	v_mov_b32_e32 v113, v0
	v_mov_b32_e32 v126, v0
	v_mov_b32_e32 v127, v0
	v_mov_b32_e32 v128, v0
	v_mov_b32_e32 v129, v0
	v_mov_b32_e32 v134, v0
	v_mov_b32_e32 v135, v0
	v_mov_b32_e32 v136, v0
	v_mov_b32_e32 v137, v0
.LBB0_1978:
	s_add_u32 s50, s48, 0xffffff00
	s_addc_u32 s51, s49, -1
	s_add_i32 s6, 0, 0x10000
	s_cmp_eq_u32 s68, 40
	s_cselect_b32 s55, s45, s51
	s_cselect_b32 s54, s44, s50
	v_add_u32_e32 v48, s6, v183
	s_cselect_b32 s53, s47, s67
	s_cselect_b32 s52, s46, s66
	s_add_i32 s26, 0, 0x14000
	ds_read_b128 v[122:125], v48
	ds_read_b128 v[130:133], v48 offset:1024
	ds_read_b128 v[138:141], v48 offset:2048
	ds_read_b128 v[142:145], v48 offset:3072
	v_add_u32_e32 v48, s26, v183
	ds_read_b128 v[146:149], v48
	ds_read_b128 v[150:153], v48 offset:1024
	ds_read_b128 v[168:171], v48 offset:2048
	ds_read_b128 v[172:175], v48 offset:3072
	v_lshl_add_u64 v[180:181], s[48:49], 0, v[164:165]
	s_add_i32 m0, s56, 0xc000
	ds_read_b128 v[176:179], v185
	ds_read_b128 v[186:189], v185 offset:1024
	ds_read_b128 v[190:193], v185 offset:2048
	ds_read_b128 v[194:197], v185 offset:3072
	ds_read_b128 v[198:201], v185 offset:4096
	ds_read_b128 v[216:219], v185 offset:5120
	ds_read_b128 v[220:223], v185 offset:6144
	ds_read_b128 v[224:227], v185 offset:7168
	global_load_lds_dwordx4 v[180:181], off
	v_lshl_add_u64 v[180:181], s[48:49], 0, v[166:167]
	s_add_i32 m0, s56, 0xe000
	s_nop 0
	global_load_lds_dwordx4 v[180:181], off
	s_waitcnt vmcnt(8)
	s_waitcnt lgkmcnt(0)
	s_barrier
	s_setprio 1
	v_mfma_f32_16x16x32_bf16 v[134:137], v[122:125], v[176:179], v[134:137]
	v_mfma_f32_16x16x32_bf16 v[126:129], v[138:141], v[176:179], v[126:129]
	v_mfma_f32_16x16x32_bf16 v[110:113], v[122:125], v[190:193], v[110:113]
	v_mfma_f32_16x16x32_bf16 v[106:109], v[138:141], v[190:193], v[106:109]
	v_mfma_f32_16x16x32_bf16 v[94:97], v[122:125], v[198:201], v[94:97]
	v_mfma_f32_16x16x32_bf16 v[90:93], v[138:141], v[198:201], v[90:93]
	v_mfma_f32_16x16x32_bf16 v[78:81], v[122:125], v[220:223], v[78:81]
	v_mfma_f32_16x16x32_bf16 v[74:77], v[138:141], v[220:223], v[74:77]
	v_mfma_f32_16x16x32_bf16 v[134:137], v[130:133], v[186:189], v[134:137]
	v_mfma_f32_16x16x32_bf16 v[126:129], v[142:145], v[186:189], v[126:129]
	v_mfma_f32_16x16x32_bf16 v[110:113], v[130:133], v[194:197], v[110:113]
	v_mfma_f32_16x16x32_bf16 v[106:109], v[142:145], v[194:197], v[106:109]
	v_mfma_f32_16x16x32_bf16 v[94:97], v[130:133], v[216:219], v[94:97]
	v_mfma_f32_16x16x32_bf16 v[90:93], v[142:145], v[216:219], v[90:93]
	v_mfma_f32_16x16x32_bf16 v[78:81], v[130:133], v[224:227], v[78:81]
	v_mfma_f32_16x16x32_bf16 v[74:77], v[142:145], v[224:227], v[74:77]
	v_mfma_f32_16x16x32_bf16 v[118:121], v[146:149], v[176:179], v[118:121]
	v_mfma_f32_16x16x32_bf16 v[114:117], v[168:171], v[176:179], v[114:117]
	v_mfma_f32_16x16x32_bf16 v[102:105], v[146:149], v[190:193], v[102:105]
	v_mfma_f32_16x16x32_bf16 v[98:101], v[168:171], v[190:193], v[98:101]
	v_mfma_f32_16x16x32_bf16 v[86:89], v[146:149], v[198:201], v[86:89]
	v_mfma_f32_16x16x32_bf16 v[82:85], v[168:171], v[198:201], v[82:85]
	v_mfma_f32_16x16x32_bf16 v[70:73], v[146:149], v[220:223], v[70:73]
	v_mfma_f32_16x16x32_bf16 v[66:69], v[168:171], v[220:223], v[66:69]
	v_mfma_f32_16x16x32_bf16 v[118:121], v[150:153], v[186:189], v[118:121]
	v_mfma_f32_16x16x32_bf16 v[114:117], v[172:175], v[186:189], v[114:117]
	v_mfma_f32_16x16x32_bf16 v[102:105], v[150:153], v[194:197], v[102:105]
	v_mfma_f32_16x16x32_bf16 v[98:101], v[172:175], v[194:197], v[98:101]
	v_mfma_f32_16x16x32_bf16 v[86:89], v[150:153], v[216:219], v[86:89]
	v_mfma_f32_16x16x32_bf16 v[82:85], v[172:175], v[216:219], v[82:85]
	v_mfma_f32_16x16x32_bf16 v[70:73], v[150:153], v[224:227], v[70:73]
	v_mfma_f32_16x16x32_bf16 v[66:69], v[172:175], v[224:227], v[66:69]
	s_setprio 0
	s_barrier
	s_add_i32 s6, s6, s24
	v_lshl_add_u64 v[180:181], s[52:53], 0, v[158:159]
	s_mov_b32 m0, s6
	ds_read_b128 v[176:179], v185 offset:16384
	ds_read_b128 v[186:189], v185 offset:17408
	ds_read_b128 v[190:193], v185 offset:18432
	ds_read_b128 v[194:197], v185 offset:19456
	ds_read_b128 v[198:201], v185 offset:20480
	ds_read_b128 v[216:219], v185 offset:21504
	ds_read_b128 v[220:223], v185 offset:22528
	ds_read_b128 v[224:227], v185 offset:23552
	global_load_lds_dwordx4 v[180:181], off
	s_add_i32 m0, s6, 0x2000
	s_add_u32 s20, s52, 0xb0000
	v_lshl_add_u64 v[202:203], s[52:53], 0, v[162:163]
	s_addc_u32 s21, s53, 0
	s_add_i32 s6, s26, s24
	global_load_lds_dwordx4 v[202:203], off
	v_lshl_add_u64 v[212:213], s[20:21], 0, v[158:159]
	s_mov_b32 m0, s6
	v_lshl_add_u64 v[214:215], s[54:55], 0, v[160:161]
	global_load_lds_dwordx4 v[212:213], off
	v_lshl_add_u64 v[212:213], s[20:21], 0, v[162:163]
	s_add_i32 m0, s6, 0x2000
	s_nop 0
	global_load_lds_dwordx4 v[212:213], off
	v_lshl_add_u64 v[212:213], s[54:55], 0, v[156:157]
	s_mov_b32 m0, s56
	s_nop 0
	global_load_lds_dwordx4 v[212:213], off
	s_mov_b32 m0, s57
	s_nop 0
	global_load_lds_dwordx4 v[214:215], off
	s_waitcnt vmcnt(8)
	s_waitcnt lgkmcnt(0)
	s_barrier
	s_setprio 1
	v_mfma_f32_16x16x32_bf16 v[62:65], v[122:125], v[176:179], v[62:65]
	v_mfma_f32_16x16x32_bf16 v[58:61], v[138:141], v[176:179], v[58:61]
	v_mfma_f32_16x16x32_bf16 v[44:47], v[122:125], v[190:193], v[44:47]
	v_mfma_f32_16x16x32_bf16 v[40:43], v[138:141], v[190:193], v[40:43]
	v_mfma_f32_16x16x32_bf16 v[28:31], v[122:125], v[198:201], v[28:31]
	v_mfma_f32_16x16x32_bf16 v[24:27], v[138:141], v[198:201], v[24:27]
	v_mfma_f32_16x16x32_bf16 v[12:15], v[122:125], v[220:223], v[12:15]
	v_mfma_f32_16x16x32_bf16 v[8:11], v[138:141], v[220:223], v[8:11]
	v_mfma_f32_16x16x32_bf16 v[62:65], v[130:133], v[186:189], v[62:65]
	v_mfma_f32_16x16x32_bf16 v[58:61], v[142:145], v[186:189], v[58:61]
	v_mfma_f32_16x16x32_bf16 v[44:47], v[130:133], v[194:197], v[44:47]
	v_mfma_f32_16x16x32_bf16 v[40:43], v[142:145], v[194:197], v[40:43]
	v_mfma_f32_16x16x32_bf16 v[28:31], v[130:133], v[216:219], v[28:31]
	v_mfma_f32_16x16x32_bf16 v[24:27], v[142:145], v[216:219], v[24:27]
	v_mfma_f32_16x16x32_bf16 v[12:15], v[130:133], v[224:227], v[12:15]
	v_mfma_f32_16x16x32_bf16 v[8:11], v[142:145], v[224:227], v[8:11]
	v_mfma_f32_16x16x32_bf16 v[54:57], v[146:149], v[176:179], v[54:57]
	v_mfma_f32_16x16x32_bf16 v[50:53], v[168:171], v[176:179], v[50:53]
	v_mfma_f32_16x16x32_bf16 v[36:39], v[146:149], v[190:193], v[36:39]
	v_mfma_f32_16x16x32_bf16 v[32:35], v[168:171], v[190:193], v[32:35]
	v_mfma_f32_16x16x32_bf16 v[20:23], v[146:149], v[198:201], v[20:23]
	v_mfma_f32_16x16x32_bf16 v[16:19], v[168:171], v[198:201], v[16:19]
	v_mfma_f32_16x16x32_bf16 v[4:7], v[146:149], v[220:223], v[4:7]
	v_mfma_f32_16x16x32_bf16 v[0:3], v[168:171], v[220:223], v[0:3]
	v_mfma_f32_16x16x32_bf16 v[54:57], v[150:153], v[186:189], v[54:57]
	v_mfma_f32_16x16x32_bf16 v[50:53], v[172:175], v[186:189], v[50:53]
	v_mfma_f32_16x16x32_bf16 v[36:39], v[150:153], v[194:197], v[36:39]
	v_mfma_f32_16x16x32_bf16 v[32:35], v[172:175], v[194:197], v[32:35]
	v_mfma_f32_16x16x32_bf16 v[20:23], v[150:153], v[216:219], v[20:23]
	v_mfma_f32_16x16x32_bf16 v[16:19], v[172:175], v[216:219], v[16:19]
	v_mfma_f32_16x16x32_bf16 v[4:7], v[150:153], v[224:227], v[4:7]
	v_mfma_f32_16x16x32_bf16 v[0:3], v[172:175], v[224:227], v[0:3]
	s_setprio 0
	s_barrier
	s_add_i32 s6, 0, 0x18000
	v_add_u32_e32 v48, s6, v183
	s_add_i32 s26, 0, 0x1c000
	ds_read_b128 v[122:125], v48
	ds_read_b128 v[130:133], v48 offset:1024
	ds_read_b128 v[138:141], v48 offset:2048
	ds_read_b128 v[142:145], v48 offset:3072
	v_add_u32_e32 v48, s26, v183
	ds_read_b128 v[146:149], v48
	ds_read_b128 v[150:153], v48 offset:1024
	ds_read_b128 v[168:171], v48 offset:2048
	ds_read_b128 v[172:175], v48 offset:3072
	s_add_u32 s20, s54, 0xb0000
	s_addc_u32 s21, s55, 0
	s_mov_b32 m0, s58
	v_lshl_add_u64 v[228:229], s[20:21], 0, v[156:157]
	ds_read_b128 v[176:179], v185 offset:32768
	ds_read_b128 v[186:189], v185 offset:33792
	ds_read_b128 v[190:193], v185 offset:34816
	ds_read_b128 v[194:197], v185 offset:35840
	ds_read_b128 v[198:201], v185 offset:36864
	ds_read_b128 v[216:219], v185 offset:37888
	ds_read_b128 v[220:223], v185 offset:38912
	ds_read_b128 v[224:227], v185 offset:39936
	global_load_lds_dwordx4 v[228:229], off
	v_lshl_add_u64 v[228:229], s[20:21], 0, v[160:161]
	s_mov_b32 m0, s59
	s_nop 0
	global_load_lds_dwordx4 v[228:229], off
	s_waitcnt vmcnt(8)
	s_waitcnt lgkmcnt(0)
	s_barrier
	s_setprio 1
	v_mfma_f32_16x16x32_bf16 v[134:137], v[122:125], v[176:179], v[134:137]
	v_mfma_f32_16x16x32_bf16 v[126:129], v[138:141], v[176:179], v[126:129]
	v_mfma_f32_16x16x32_bf16 v[110:113], v[122:125], v[190:193], v[110:113]
	v_mfma_f32_16x16x32_bf16 v[106:109], v[138:141], v[190:193], v[106:109]
	v_mfma_f32_16x16x32_bf16 v[94:97], v[122:125], v[198:201], v[94:97]
	v_mfma_f32_16x16x32_bf16 v[90:93], v[138:141], v[198:201], v[90:93]
	v_mfma_f32_16x16x32_bf16 v[78:81], v[122:125], v[220:223], v[78:81]
	v_mfma_f32_16x16x32_bf16 v[74:77], v[138:141], v[220:223], v[74:77]
	v_mfma_f32_16x16x32_bf16 v[134:137], v[130:133], v[186:189], v[134:137]
	v_mfma_f32_16x16x32_bf16 v[126:129], v[142:145], v[186:189], v[126:129]
	v_mfma_f32_16x16x32_bf16 v[110:113], v[130:133], v[194:197], v[110:113]
	v_mfma_f32_16x16x32_bf16 v[106:109], v[142:145], v[194:197], v[106:109]
	v_mfma_f32_16x16x32_bf16 v[94:97], v[130:133], v[216:219], v[94:97]
	v_mfma_f32_16x16x32_bf16 v[90:93], v[142:145], v[216:219], v[90:93]
	v_mfma_f32_16x16x32_bf16 v[78:81], v[130:133], v[224:227], v[78:81]
	v_mfma_f32_16x16x32_bf16 v[74:77], v[142:145], v[224:227], v[74:77]
	v_mfma_f32_16x16x32_bf16 v[118:121], v[146:149], v[176:179], v[118:121]
	v_mfma_f32_16x16x32_bf16 v[114:117], v[168:171], v[176:179], v[114:117]
	v_mfma_f32_16x16x32_bf16 v[102:105], v[146:149], v[190:193], v[102:105]
	v_mfma_f32_16x16x32_bf16 v[98:101], v[168:171], v[190:193], v[98:101]
	v_mfma_f32_16x16x32_bf16 v[86:89], v[146:149], v[198:201], v[86:89]
	v_mfma_f32_16x16x32_bf16 v[82:85], v[168:171], v[198:201], v[82:85]
	v_mfma_f32_16x16x32_bf16 v[70:73], v[146:149], v[220:223], v[70:73]
	v_mfma_f32_16x16x32_bf16 v[66:69], v[168:171], v[220:223], v[66:69]
	v_mfma_f32_16x16x32_bf16 v[118:121], v[150:153], v[186:189], v[118:121]
	v_mfma_f32_16x16x32_bf16 v[114:117], v[172:175], v[186:189], v[114:117]
	v_mfma_f32_16x16x32_bf16 v[102:105], v[150:153], v[194:197], v[102:105]
	v_mfma_f32_16x16x32_bf16 v[98:101], v[172:175], v[194:197], v[98:101]
	v_mfma_f32_16x16x32_bf16 v[86:89], v[150:153], v[216:219], v[86:89]
	v_mfma_f32_16x16x32_bf16 v[82:85], v[172:175], v[216:219], v[82:85]
	v_mfma_f32_16x16x32_bf16 v[70:73], v[150:153], v[224:227], v[70:73]
	v_mfma_f32_16x16x32_bf16 v[66:69], v[172:175], v[224:227], v[66:69]
	s_setprio 0
	s_barrier
	s_add_i32 s6, s6, s24
	v_lshl_add_u64 v[180:181], v[180:181], 0, s[30:31]
	s_mov_b32 m0, s6
	ds_read_b128 v[176:179], v185 offset:49152
	ds_read_b128 v[186:189], v185 offset:50176
	ds_read_b128 v[190:193], v185 offset:51200
	ds_read_b128 v[194:197], v185 offset:52224
	ds_read_b128 v[198:201], v185 offset:53248
	ds_read_b128 v[216:219], v185 offset:54272
	ds_read_b128 v[220:223], v185 offset:55296
	ds_read_b128 v[224:227], v185 offset:56320
	global_load_lds_dwordx4 v[180:181], off
	s_add_i32 m0, s6, 0x2000
	s_add_u32 s20, s52, 0xb0080
	v_lshl_add_u64 v[180:181], v[202:203], 0, s[30:31]
	s_addc_u32 s21, s53, 0
	s_add_i32 s6, s26, s24
	global_load_lds_dwordx4 v[180:181], off
	v_lshl_add_u64 v[180:181], s[20:21], 0, v[158:159]
	s_mov_b32 m0, s6
	s_nop 0
	global_load_lds_dwordx4 v[180:181], off
	v_lshl_add_u64 v[180:181], s[20:21], 0, v[162:163]
	s_add_i32 m0, s6, 0x2000
	s_nop 0
	global_load_lds_dwordx4 v[180:181], off
	v_lshl_add_u64 v[180:181], v[212:213], 0, s[30:31]
	s_mov_b32 m0, s60
	s_nop 0
	global_load_lds_dwordx4 v[180:181], off
	v_lshl_add_u64 v[180:181], v[214:215], 0, s[30:31]
	s_mov_b32 m0, s61
	s_nop 0
	global_load_lds_dwordx4 v[180:181], off
	s_waitcnt vmcnt(8)
	s_waitcnt lgkmcnt(0)
	s_barrier
	s_setprio 1
	v_mfma_f32_16x16x32_bf16 v[62:65], v[122:125], v[176:179], v[62:65]
	v_mfma_f32_16x16x32_bf16 v[58:61], v[138:141], v[176:179], v[58:61]
	v_mfma_f32_16x16x32_bf16 v[44:47], v[122:125], v[190:193], v[44:47]
	v_mfma_f32_16x16x32_bf16 v[40:43], v[138:141], v[190:193], v[40:43]
	v_mfma_f32_16x16x32_bf16 v[28:31], v[122:125], v[198:201], v[28:31]
	v_mfma_f32_16x16x32_bf16 v[24:27], v[138:141], v[198:201], v[24:27]
	v_mfma_f32_16x16x32_bf16 v[12:15], v[122:125], v[220:223], v[12:15]
	v_mfma_f32_16x16x32_bf16 v[8:11], v[138:141], v[220:223], v[8:11]
	v_mfma_f32_16x16x32_bf16 v[62:65], v[130:133], v[186:189], v[62:65]
	v_mfma_f32_16x16x32_bf16 v[58:61], v[142:145], v[186:189], v[58:61]
	v_mfma_f32_16x16x32_bf16 v[44:47], v[130:133], v[194:197], v[44:47]
	v_mfma_f32_16x16x32_bf16 v[40:43], v[142:145], v[194:197], v[40:43]
	v_mfma_f32_16x16x32_bf16 v[28:31], v[130:133], v[216:219], v[28:31]
	v_mfma_f32_16x16x32_bf16 v[24:27], v[142:145], v[216:219], v[24:27]
	v_mfma_f32_16x16x32_bf16 v[12:15], v[130:133], v[224:227], v[12:15]
	v_mfma_f32_16x16x32_bf16 v[8:11], v[142:145], v[224:227], v[8:11]
	v_mfma_f32_16x16x32_bf16 v[54:57], v[146:149], v[176:179], v[54:57]
	v_mfma_f32_16x16x32_bf16 v[50:53], v[168:171], v[176:179], v[50:53]
	v_mfma_f32_16x16x32_bf16 v[36:39], v[146:149], v[190:193], v[36:39]
	v_mfma_f32_16x16x32_bf16 v[32:35], v[168:171], v[190:193], v[32:35]
	v_mfma_f32_16x16x32_bf16 v[20:23], v[146:149], v[198:201], v[20:23]
	v_mfma_f32_16x16x32_bf16 v[16:19], v[168:171], v[198:201], v[16:19]
	v_mfma_f32_16x16x32_bf16 v[4:7], v[146:149], v[220:223], v[4:7]
	v_mfma_f32_16x16x32_bf16 v[0:3], v[168:171], v[220:223], v[0:3]
	v_mfma_f32_16x16x32_bf16 v[54:57], v[150:153], v[186:189], v[54:57]
	v_mfma_f32_16x16x32_bf16 v[50:53], v[172:175], v[186:189], v[50:53]
	v_mfma_f32_16x16x32_bf16 v[36:39], v[150:153], v[194:197], v[36:39]
	v_mfma_f32_16x16x32_bf16 v[32:35], v[172:175], v[194:197], v[32:35]
	v_mfma_f32_16x16x32_bf16 v[20:23], v[150:153], v[216:219], v[20:23]
	v_mfma_f32_16x16x32_bf16 v[16:19], v[172:175], v[216:219], v[16:19]
	v_mfma_f32_16x16x32_bf16 v[4:7], v[150:153], v[224:227], v[4:7]
	v_mfma_f32_16x16x32_bf16 v[0:3], v[172:175], v[224:227], v[0:3]
	s_setprio 0
	s_barrier
	s_add_i32 s68, s68, 2
	s_add_u32 s66, s66, 0xffffff00
	s_addc_u32 s67, s67, -1
	s_cmp_gt_u32 s68, 41
	s_mov_b64 s[48:49], s[50:51]
	s_cbranch_scc0 .LBB0_1978
	s_and_b64 vcc, exec, s[42:43]
	s_cbranch_vccz .LBB0_1981
	s_barrier
